# residual GEMM fused-norm epilogue: new-residual stores issued before the row-sum exchange poll (write burst overlaps the exchange latency)
# speedup vs baseline: 1.0462x; 1.0049x over previous
.Lrn_noslot:
	s_waitcnt vmcnt(0)
	s_barrier
	s_cmp_lg_u32 s25, 0
	s_cbranch_scc1 .Lrn_xst
	v_readlane_b32 s30, v253, 42
	v_readlane_b32 s31, v253, 43
	s_lshl_b32 s25, s38, 6
	s_add_i32 s25, s25, s76
	s_lshl_b32 s25, s25, 2
	s_add_i32 s25, s25, 0x8000
	s_add_u32 s30, s30, s25
	s_addc_u32 s31, s31, 0
	s_mov_b64 exec, 1
	v_mov_b32_e32 v216, 1
	s_nop 4
	global_atomic_add v1, v216, s[30:31]
	s_mov_b64 exec, -1
	s_mov_b32 s25, 0
.Lrn_xst:
	s_cmp_eq_u32 s38, 7
	s_cbranch_scc1 .Lrn_xst_done
	v_lshl_add_u64 v[242:243], s[10:11], 0, v[226:227]
	v_lshl_add_u64 v[242:243], v[242:243], 0, v[228:229]
	v_mov_b32_e32 v246, v242
	v_mov_b32_e32 v247, v243
	global_store_dwordx4 v[246:247], v[130:133], off offset:0
	global_store_dwordx4 v[246:247], v[126:129], off offset:64
	global_store_dwordx4 v[246:247], v[122:125], off offset:512
	global_store_dwordx4 v[246:247], v[118:121], off offset:576
	v_add_co_u32_e32 v246, vcc, 0x10000, v242
	v_addc_co_u32_e32 v247, vcc, 0, v243, vcc
	global_store_dwordx4 v[246:247], v[114:117], off offset:0
	global_store_dwordx4 v[246:247], v[110:113], off offset:64
	global_store_dwordx4 v[246:247], v[106:109], off offset:512
	global_store_dwordx4 v[246:247], v[102:105], off offset:576
	v_add_co_u32_e32 v246, vcc, 0x20000, v242
	v_addc_co_u32_e32 v247, vcc, 0, v243, vcc
	global_store_dwordx4 v[246:247], v[98:101], off offset:0
	global_store_dwordx4 v[246:247], v[94:97], off offset:64
	global_store_dwordx4 v[246:247], v[90:93], off offset:512
	global_store_dwordx4 v[246:247], v[86:89], off offset:576
	v_add_co_u32_e32 v246, vcc, 0x30000, v242
	v_addc_co_u32_e32 v247, vcc, 0, v243, vcc
	global_store_dwordx4 v[246:247], v[82:85], off offset:0
	global_store_dwordx4 v[246:247], v[78:81], off offset:64
	global_store_dwordx4 v[246:247], v[74:77], off offset:512
	global_store_dwordx4 v[246:247], v[70:73], off offset:576
	v_add_co_u32_e32 v246, vcc, 0x80000, v242
	v_addc_co_u32_e32 v247, vcc, 0, v243, vcc
	global_store_dwordx4 v[246:247], v[66:69], off offset:0
	global_store_dwordx4 v[246:247], v[62:65], off offset:64
	global_store_dwordx4 v[246:247], v[58:61], off offset:512
	global_store_dwordx4 v[246:247], v[54:57], off offset:576
	v_add_co_u32_e32 v246, vcc, 0x90000, v242
	v_addc_co_u32_e32 v247, vcc, 0, v243, vcc
	global_store_dwordx4 v[246:247], v[50:53], off offset:0
	global_store_dwordx4 v[246:247], v[46:49], off offset:64
	global_store_dwordx4 v[246:247], v[42:45], off offset:512
	global_store_dwordx4 v[246:247], v[38:41], off offset:576
	v_add_co_u32_e32 v246, vcc, 0xa0000, v242
	v_addc_co_u32_e32 v247, vcc, 0, v243, vcc
	global_store_dwordx4 v[246:247], v[34:37], off offset:0
	global_store_dwordx4 v[246:247], v[30:33], off offset:64
	global_store_dwordx4 v[246:247], v[26:29], off offset:512
	global_store_dwordx4 v[246:247], v[22:25], off offset:576
	v_add_co_u32_e32 v246, vcc, 0xb0000, v242
	v_addc_co_u32_e32 v247, vcc, 0, v243, vcc
	global_store_dwordx4 v[246:247], v[18:21], off offset:0
	global_store_dwordx4 v[246:247], v[14:17], off offset:64
	global_store_dwordx4 v[246:247], v[10:13], off offset:512
	global_store_dwordx4 v[246:247], v[6:9], off offset:576
.Lrn_xst_done:
	s_cmp_lg_u32 s25, 0
	s_cbranch_scc1 .Lrn_nopoll
	s_mov_b64 exec, 1

.Lrn_nors:
	s_waitcnt lgkmcnt(0)
	s_barrier
	v_add_u32_e32 v211, s62, v223
	v_lshlrev_b32_e32 v210, 2, v211
	v_add_u32_e32 v210, 0x22000, v210
	ds_read_b32 v182, v210 offset:0
	ds_read_b32 v184, v210 offset:64
	ds_read_b32 v186, v210 offset:128
	ds_read_b32 v188, v210 offset:192
	ds_read_b32 v190, v210 offset:512
	ds_read_b32 v192, v210 offset:576
	ds_read_b32 v194, v210 offset:640
	ds_read_b32 v196, v210 offset:704
	v_pk_add_f32 v[166:167], v[166:167], 1.0 op_sel_hi:[1,0]
	v_pk_mul_f32 v[134:135], v[134:135], v[166:167]
	v_pk_add_f32 v[168:169], v[168:169], 1.0 op_sel_hi:[1,0]
	v_pk_mul_f32 v[136:137], v[136:137], v[168:169]
	v_pk_add_f32 v[170:171], v[170:171], 1.0 op_sel_hi:[1,0]
	v_pk_mul_f32 v[138:139], v[138:139], v[170:171]
	v_pk_add_f32 v[172:173], v[172:173], 1.0 op_sel_hi:[1,0]
	v_pk_mul_f32 v[140:141], v[140:141], v[172:173]
	v_pk_add_f32 v[174:175], v[174:175], 1.0 op_sel_hi:[1,0]
	v_pk_mul_f32 v[142:143], v[142:143], v[174:175]
	v_pk_add_f32 v[176:177], v[176:177], 1.0 op_sel_hi:[1,0]
	v_pk_mul_f32 v[144:145], v[144:145], v[176:177]
	v_pk_add_f32 v[178:179], v[178:179], 1.0 op_sel_hi:[1,0]
	v_pk_mul_f32 v[146:147], v[146:147], v[178:179]
	v_pk_add_f32 v[180:181], v[180:181], 1.0 op_sel_hi:[1,0]
	v_pk_mul_f32 v[148:149], v[148:149], v[180:181]
	v_lshl_add_u64 v[242:243], s[10:11], 0, v[226:227]
	v_lshl_add_u64 v[242:243], v[242:243], 0, v[228:229]
	v_readlane_b32 s36, v253, 42
	v_readlane_b32 s37, v253, 43
	s_add_u32 s36, s36, 0x7400000
	s_addc_u32 s37, s37, 0
	v_lshrrev_b64 v[244:245], 1, v[226:227]
	v_lshrrev_b64 v[246:247], 1, v[228:229]
	v_lshl_add_u64 v[244:245], s[36:37], 0, v[244:245]
	v_lshl_add_u64 v[244:245], v[244:245], 0, v[246:247]
	s_mov_b32 s31, 0
	s_waitcnt lgkmcnt(0)
	s_cmp_eq_u32 s38, 7
	s_cbranch_scc1 .Lrn_final_out
	s_mov_b32 s30, 0x0
	v_lshl_add_u64 v[248:249], v[244:245], 0, s[30:31]
	v_pk_mul_f32 v[198:199], v[130:131], v[182:183] op_sel_hi:[1,0]
	v_pk_fma_f32 v[198:199], v[198:199], v[134:135], v[150:151]
	v_pk_mul_f32 v[200:201], v[132:133], v[182:183] op_sel_hi:[1,0]
	v_pk_fma_f32 v[200:201], v[200:201], v[136:137], v[152:153]
	v_cvt_pk_bf16_f32 v214, v198, v199
	v_cvt_pk_bf16_f32 v215, v200, v201
	global_store_dwordx2 v[248:249], v[214:215], off offset:0
	v_pk_mul_f32 v[202:203], v[126:127], v[182:183] op_sel_hi:[1,0]
	v_pk_fma_f32 v[202:203], v[202:203], v[138:139], v[154:155]
	v_pk_mul_f32 v[204:205], v[128:129], v[182:183] op_sel_hi:[1,0]
	v_pk_fma_f32 v[204:205], v[204:205], v[140:141], v[156:157]
	v_cvt_pk_bf16_f32 v216, v202, v203
	v_cvt_pk_bf16_f32 v217, v204, v205
	global_store_dwordx2 v[248:249], v[216:217], off offset:32
	v_pk_mul_f32 v[198:199], v[122:123], v[182:183] op_sel_hi:[1,0]
	v_pk_fma_f32 v[198:199], v[198:199], v[142:143], v[158:159]
	v_pk_mul_f32 v[200:201], v[124:125], v[182:183] op_sel_hi:[1,0]
	v_pk_fma_f32 v[200:201], v[200:201], v[144:145], v[160:161]
	v_cvt_pk_bf16_f32 v214, v198, v199
	v_cvt_pk_bf16_f32 v215, v200, v201
	global_store_dwordx2 v[248:249], v[214:215], off offset:256
	v_pk_mul_f32 v[202:203], v[118:119], v[182:183] op_sel_hi:[1,0]
	v_pk_fma_f32 v[202:203], v[202:203], v[146:147], v[162:163]
	v_pk_mul_f32 v[204:205], v[120:121], v[182:183] op_sel_hi:[1,0]
	v_pk_fma_f32 v[204:205], v[204:205], v[148:149], v[164:165]
	v_cvt_pk_bf16_f32 v216, v202, v203
	v_cvt_pk_bf16_f32 v217, v204, v205
	global_store_dwordx2 v[248:249], v[216:217], off offset:288
	s_mov_b32 s30, 0x8000
	v_lshl_add_u64 v[248:249], v[244:245], 0, s[30:31]
	v_pk_mul_f32 v[198:199], v[114:115], v[184:185] op_sel_hi:[1,0]
	v_pk_fma_f32 v[198:199], v[198:199], v[134:135], v[150:151]
	v_pk_mul_f32 v[200:201], v[116:117], v[184:185] op_sel_hi:[1,0]
	v_pk_fma_f32 v[200:201], v[200:201], v[136:137], v[152:153]
	v_cvt_pk_bf16_f32 v214, v198, v199
	v_cvt_pk_bf16_f32 v215, v200, v201
	global_store_dwordx2 v[248:249], v[214:215], off offset:0
	v_pk_mul_f32 v[202:203], v[110:111], v[184:185] op_sel_hi:[1,0]
	v_pk_fma_f32 v[202:203], v[202:203], v[138:139], v[154:155]
	v_pk_mul_f32 v[204:205], v[112:113], v[184:185] op_sel_hi:[1,0]
	v_pk_fma_f32 v[204:205], v[204:205], v[140:141], v[156:157]
	v_cvt_pk_bf16_f32 v216, v202, v203
	v_cvt_pk_bf16_f32 v217, v204, v205
	global_store_dwordx2 v[248:249], v[216:217], off offset:32
	v_pk_mul_f32 v[198:199], v[106:107], v[184:185] op_sel_hi:[1,0]
	v_pk_fma_f32 v[198:199], v[198:199], v[142:143], v[158:159]
	v_pk_mul_f32 v[200:201], v[108:109], v[184:185] op_sel_hi:[1,0]
	v_pk_fma_f32 v[200:201], v[200:201], v[144:145], v[160:161]
	v_cvt_pk_bf16_f32 v214, v198, v199
	v_cvt_pk_bf16_f32 v215, v200, v201
	global_store_dwordx2 v[248:249], v[214:215], off offset:256
	v_pk_mul_f32 v[202:203], v[102:103], v[184:185] op_sel_hi:[1,0]
	v_pk_fma_f32 v[202:203], v[202:203], v[146:147], v[162:163]
	v_pk_mul_f32 v[204:205], v[104:105], v[184:185] op_sel_hi:[1,0]
	v_pk_fma_f32 v[204:205], v[204:205], v[148:149], v[164:165]
	v_cvt_pk_bf16_f32 v216, v202, v203
	v_cvt_pk_bf16_f32 v217, v204, v205
	global_store_dwordx2 v[248:249], v[216:217], off offset:288
	s_mov_b32 s30, 0x10000
	v_lshl_add_u64 v[248:249], v[244:245], 0, s[30:31]
	v_pk_mul_f32 v[198:199], v[98:99], v[186:187] op_sel_hi:[1,0]
	v_pk_fma_f32 v[198:199], v[198:199], v[134:135], v[150:151]
	v_pk_mul_f32 v[200:201], v[100:101], v[186:187] op_sel_hi:[1,0]
	v_pk_fma_f32 v[200:201], v[200:201], v[136:137], v[152:153]
	v_cvt_pk_bf16_f32 v214, v198, v199
	v_cvt_pk_bf16_f32 v215, v200, v201
	global_store_dwordx2 v[248:249], v[214:215], off offset:0
	v_pk_mul_f32 v[202:203], v[94:95], v[186:187] op_sel_hi:[1,0]
	v_pk_fma_f32 v[202:203], v[202:203], v[138:139], v[154:155]
	v_pk_mul_f32 v[204:205], v[96:97], v[186:187] op_sel_hi:[1,0]
	v_pk_fma_f32 v[204:205], v[204:205], v[140:141], v[156:157]
	v_cvt_pk_bf16_f32 v216, v202, v203
	v_cvt_pk_bf16_f32 v217, v204, v205
	global_store_dwordx2 v[248:249], v[216:217], off offset:32
	v_pk_mul_f32 v[198:199], v[90:91], v[186:187] op_sel_hi:[1,0]
	v_pk_fma_f32 v[198:199], v[198:199], v[142:143], v[158:159]
	v_pk_mul_f32 v[200:201], v[92:93], v[186:187] op_sel_hi:[1,0]
	v_pk_fma_f32 v[200:201], v[200:201], v[144:145], v[160:161]
	v_cvt_pk_bf16_f32 v214, v198, v199
	v_cvt_pk_bf16_f32 v215, v200, v201
	global_store_dwordx2 v[248:249], v[214:215], off offset:256
	v_pk_mul_f32 v[202:203], v[86:87], v[186:187] op_sel_hi:[1,0]
	v_pk_fma_f32 v[202:203], v[202:203], v[146:147], v[162:163]
	v_pk_mul_f32 v[204:205], v[88:89], v[186:187] op_sel_hi:[1,0]
	v_pk_fma_f32 v[204:205], v[204:205], v[148:149], v[164:165]
	v_cvt_pk_bf16_f32 v216, v202, v203
	v_cvt_pk_bf16_f32 v217, v204, v205
	global_store_dwordx2 v[248:249], v[216:217], off offset:288
	s_mov_b32 s30, 0x18000
	v_lshl_add_u64 v[248:249], v[244:245], 0, s[30:31]
	v_pk_mul_f32 v[198:199], v[82:83], v[188:189] op_sel_hi:[1,0]
	v_pk_fma_f32 v[198:199], v[198:199], v[134:135], v[150:151]
	v_pk_mul_f32 v[200:201], v[84:85], v[188:189] op_sel_hi:[1,0]
	v_pk_fma_f32 v[200:201], v[200:201], v[136:137], v[152:153]
	v_cvt_pk_bf16_f32 v214, v198, v199
	v_cvt_pk_bf16_f32 v215, v200, v201
	global_store_dwordx2 v[248:249], v[214:215], off offset:0
	v_pk_mul_f32 v[202:203], v[78:79], v[188:189] op_sel_hi:[1,0]
	v_pk_fma_f32 v[202:203], v[202:203], v[138:139], v[154:155]
	v_pk_mul_f32 v[204:205], v[80:81], v[188:189] op_sel_hi:[1,0]
	v_pk_fma_f32 v[204:205], v[204:205], v[140:141], v[156:157]
	v_cvt_pk_bf16_f32 v216, v202, v203
	v_cvt_pk_bf16_f32 v217, v204, v205
	global_store_dwordx2 v[248:249], v[216:217], off offset:32
	v_pk_mul_f32 v[198:199], v[74:75], v[188:189] op_sel_hi:[1,0]
	v_pk_fma_f32 v[198:199], v[198:199], v[142:143], v[158:159]
	v_pk_mul_f32 v[200:201], v[76:77], v[188:189] op_sel_hi:[1,0]
	v_pk_fma_f32 v[200:201], v[200:201], v[144:145], v[160:161]
	v_cvt_pk_bf16_f32 v214, v198, v199
	v_cvt_pk_bf16_f32 v215, v200, v201
	global_store_dwordx2 v[248:249], v[214:215], off offset:256
	v_pk_mul_f32 v[202:203], v[70:71], v[188:189] op_sel_hi:[1,0]
	v_pk_fma_f32 v[202:203], v[202:203], v[146:147], v[162:163]
	v_pk_mul_f32 v[204:205], v[72:73], v[188:189] op_sel_hi:[1,0]
	v_pk_fma_f32 v[204:205], v[204:205], v[148:149], v[164:165]
	v_cvt_pk_bf16_f32 v216, v202, v203
	v_cvt_pk_bf16_f32 v217, v204, v205
	global_store_dwordx2 v[248:249], v[216:217], off offset:288
	s_mov_b32 s30, 0x40000
	v_lshl_add_u64 v[248:249], v[244:245], 0, s[30:31]
	v_pk_mul_f32 v[198:199], v[66:67], v[190:191] op_sel_hi:[1,0]
	v_pk_fma_f32 v[198:199], v[198:199], v[134:135], v[150:151]
	v_pk_mul_f32 v[200:201], v[68:69], v[190:191] op_sel_hi:[1,0]
	v_pk_fma_f32 v[200:201], v[200:201], v[136:137], v[152:153]
	v_cvt_pk_bf16_f32 v214, v198, v199
	v_cvt_pk_bf16_f32 v215, v200, v201
	global_store_dwordx2 v[248:249], v[214:215], off offset:0
	v_pk_mul_f32 v[202:203], v[62:63], v[190:191] op_sel_hi:[1,0]
	v_pk_fma_f32 v[202:203], v[202:203], v[138:139], v[154:155]
	v_pk_mul_f32 v[204:205], v[64:65], v[190:191] op_sel_hi:[1,0]
	v_pk_fma_f32 v[204:205], v[204:205], v[140:141], v[156:157]
	v_cvt_pk_bf16_f32 v216, v202, v203
	v_cvt_pk_bf16_f32 v217, v204, v205
	global_store_dwordx2 v[248:249], v[216:217], off offset:32
	v_pk_mul_f32 v[198:199], v[58:59], v[190:191] op_sel_hi:[1,0]
	v_pk_fma_f32 v[198:199], v[198:199], v[142:143], v[158:159]
	v_pk_mul_f32 v[200:201], v[60:61], v[190:191] op_sel_hi:[1,0]
	v_pk_fma_f32 v[200:201], v[200:201], v[144:145], v[160:161]
	v_cvt_pk_bf16_f32 v214, v198, v199
	v_cvt_pk_bf16_f32 v215, v200, v201
	global_store_dwordx2 v[248:249], v[214:215], off offset:256
	v_pk_mul_f32 v[202:203], v[54:55], v[190:191] op_sel_hi:[1,0]
	v_pk_fma_f32 v[202:203], v[202:203], v[146:147], v[162:163]
	v_pk_mul_f32 v[204:205], v[56:57], v[190:191] op_sel_hi:[1,0]
	v_pk_fma_f32 v[204:205], v[204:205], v[148:149], v[164:165]
	v_cvt_pk_bf16_f32 v216, v202, v203
	v_cvt_pk_bf16_f32 v217, v204, v205
	global_store_dwordx2 v[248:249], v[216:217], off offset:288
	s_mov_b32 s30, 0x48000
	v_lshl_add_u64 v[248:249], v[244:245], 0, s[30:31]
	v_pk_mul_f32 v[198:199], v[50:51], v[192:193] op_sel_hi:[1,0]
	v_pk_fma_f32 v[198:199], v[198:199], v[134:135], v[150:151]
	v_pk_mul_f32 v[200:201], v[52:53], v[192:193] op_sel_hi:[1,0]
	v_pk_fma_f32 v[200:201], v[200:201], v[136:137], v[152:153]
	v_cvt_pk_bf16_f32 v214, v198, v199
	v_cvt_pk_bf16_f32 v215, v200, v201
	global_store_dwordx2 v[248:249], v[214:215], off offset:0
	v_pk_mul_f32 v[202:203], v[46:47], v[192:193] op_sel_hi:[1,0]
	v_pk_fma_f32 v[202:203], v[202:203], v[138:139], v[154:155]
	v_pk_mul_f32 v[204:205], v[48:49], v[192:193] op_sel_hi:[1,0]
	v_pk_fma_f32 v[204:205], v[204:205], v[140:141], v[156:157]
	v_cvt_pk_bf16_f32 v216, v202, v203
	v_cvt_pk_bf16_f32 v217, v204, v205
	global_store_dwordx2 v[248:249], v[216:217], off offset:32
	v_pk_mul_f32 v[198:199], v[42:43], v[192:193] op_sel_hi:[1,0]
	v_pk_fma_f32 v[198:199], v[198:199], v[142:143], v[158:159]
	v_pk_mul_f32 v[200:201], v[44:45], v[192:193] op_sel_hi:[1,0]
	v_pk_fma_f32 v[200:201], v[200:201], v[144:145], v[160:161]
	v_cvt_pk_bf16_f32 v214, v198, v199
	v_cvt_pk_bf16_f32 v215, v200, v201
	global_store_dwordx2 v[248:249], v[214:215], off offset:256
	v_pk_mul_f32 v[202:203], v[38:39], v[192:193] op_sel_hi:[1,0]
	v_pk_fma_f32 v[202:203], v[202:203], v[146:147], v[162:163]
	v_pk_mul_f32 v[204:205], v[40:41], v[192:193] op_sel_hi:[1,0]
	v_pk_fma_f32 v[204:205], v[204:205], v[148:149], v[164:165]
	v_cvt_pk_bf16_f32 v216, v202, v203
	v_cvt_pk_bf16_f32 v217, v204, v205
	global_store_dwordx2 v[248:249], v[216:217], off offset:288
	s_mov_b32 s30, 0x50000
	v_lshl_add_u64 v[248:249], v[244:245], 0, s[30:31]
	v_pk_mul_f32 v[198:199], v[34:35], v[194:195] op_sel_hi:[1,0]
	v_pk_fma_f32 v[198:199], v[198:199], v[134:135], v[150:151]
	v_pk_mul_f32 v[200:201], v[36:37], v[194:195] op_sel_hi:[1,0]
	v_pk_fma_f32 v[200:201], v[200:201], v[136:137], v[152:153]
	v_cvt_pk_bf16_f32 v214, v198, v199
	v_cvt_pk_bf16_f32 v215, v200, v201
	global_store_dwordx2 v[248:249], v[214:215], off offset:0
	v_pk_mul_f32 v[202:203], v[30:31], v[194:195] op_sel_hi:[1,0]
	v_pk_fma_f32 v[202:203], v[202:203], v[138:139], v[154:155]
	v_pk_mul_f32 v[204:205], v[32:33], v[194:195] op_sel_hi:[1,0]
	v_pk_fma_f32 v[204:205], v[204:205], v[140:141], v[156:157]
	v_cvt_pk_bf16_f32 v216, v202, v203
	v_cvt_pk_bf16_f32 v217, v204, v205
	global_store_dwordx2 v[248:249], v[216:217], off offset:32
	v_pk_mul_f32 v[198:199], v[26:27], v[194:195] op_sel_hi:[1,0]
	v_pk_fma_f32 v[198:199], v[198:199], v[142:143], v[158:159]
	v_pk_mul_f32 v[200:201], v[28:29], v[194:195] op_sel_hi:[1,0]
	v_pk_fma_f32 v[200:201], v[200:201], v[144:145], v[160:161]
	v_cvt_pk_bf16_f32 v214, v198, v199
	v_cvt_pk_bf16_f32 v215, v200, v201
	global_store_dwordx2 v[248:249], v[214:215], off offset:256
	v_pk_mul_f32 v[202:203], v[22:23], v[194:195] op_sel_hi:[1,0]
	v_pk_fma_f32 v[202:203], v[202:203], v[146:147], v[162:163]
	v_pk_mul_f32 v[204:205], v[24:25], v[194:195] op_sel_hi:[1,0]
	v_pk_fma_f32 v[204:205], v[204:205], v[148:149], v[164:165]
	v_cvt_pk_bf16_f32 v216, v202, v203
	v_cvt_pk_bf16_f32 v217, v204, v205
	global_store_dwordx2 v[248:249], v[216:217], off offset:288
	s_mov_b32 s30, 0x58000
	v_lshl_add_u64 v[248:249], v[244:245], 0, s[30:31]
	v_pk_mul_f32 v[198:199], v[18:19], v[196:197] op_sel_hi:[1,0]
	v_pk_fma_f32 v[198:199], v[198:199], v[134:135], v[150:151]
	v_pk_mul_f32 v[200:201], v[20:21], v[196:197] op_sel_hi:[1,0]
	v_pk_fma_f32 v[200:201], v[200:201], v[136:137], v[152:153]
	v_cvt_pk_bf16_f32 v214, v198, v199
	v_cvt_pk_bf16_f32 v215, v200, v201
	global_store_dwordx2 v[248:249], v[214:215], off offset:0
	v_pk_mul_f32 v[202:203], v[14:15], v[196:197] op_sel_hi:[1,0]
	v_pk_fma_f32 v[202:203], v[202:203], v[138:139], v[154:155]
	v_pk_mul_f32 v[204:205], v[16:17], v[196:197] op_sel_hi:[1,0]
	v_pk_fma_f32 v[204:205], v[204:205], v[140:141], v[156:157]
	v_cvt_pk_bf16_f32 v216, v202, v203
	v_cvt_pk_bf16_f32 v217, v204, v205
	global_store_dwordx2 v[248:249], v[216:217], off offset:32
	v_pk_mul_f32 v[198:199], v[10:11], v[196:197] op_sel_hi:[1,0]
	v_pk_fma_f32 v[198:199], v[198:199], v[142:143], v[158:159]
	v_pk_mul_f32 v[200:201], v[12:13], v[196:197] op_sel_hi:[1,0]
	v_pk_fma_f32 v[200:201], v[200:201], v[144:145], v[160:161]
	v_cvt_pk_bf16_f32 v214, v198, v199
	v_cvt_pk_bf16_f32 v215, v200, v201
	global_store_dwordx2 v[248:249], v[214:215], off offset:256
	v_pk_mul_f32 v[202:203], v[6:7], v[196:197] op_sel_hi:[1,0]
	v_pk_fma_f32 v[202:203], v[202:203], v[146:147], v[162:163]
	v_pk_mul_f32 v[204:205], v[8:9], v[196:197] op_sel_hi:[1,0]
	v_pk_fma_f32 v[204:205], v[204:205], v[148:149], v[164:165]
	v_cvt_pk_bf16_f32 v216, v202, v203
	v_cvt_pk_bf16_f32 v217, v204, v205
	global_store_dwordx2 v[248:249], v[216:217], off offset:288
	s_branch .Lrn_out_done
